# converted bf16 weights stored with nt (consumed two barriers later by every XCD, no reason to stay dirty in this XCD L2)
# speedup vs baseline: 1.0033x; 1.0033x over previous
.LBB0_234:
	s_cmpk_lt_i32 s19, 0x300
	s_cselect_b32 s11, 48, 32
	v_cvt_f32_ubyte0_e32 v35, s11
	v_rcp_iflag_f32_e32 v35, v35
	s_cselect_b32 s5, s97, s77
	s_cselect_b32 s4, s89, s76
	s_cselect_b32 s10, 0, 0xfffffd00
	v_mul_f32_e32 v35, 0x4f7ffffe, v35
	v_cvt_u32_f32_e32 v35, v35
	s_sub_i32 s21, 0, s11
	s_add_i32 s10, s10, s19
	s_abs_i32 s20, s10
	v_readfirstlane_b32 s22, v35
	s_mul_i32 s21, s21, s22
	s_mul_hi_u32 s21, s22, s21
	s_add_i32 s22, s22, s21
	s_mul_hi_u32 s21, s20, s22
	s_mul_i32 s22, s21, s11
	s_sub_i32 s20, s20, s22
	s_ashr_i32 s19, s10, 31
	s_add_i32 s22, s21, 1
	s_sub_i32 s23, s20, s11
	s_cmp_ge_u32 s20, s11
	s_cselect_b32 s21, s22, s21
	s_cselect_b32 s20, s23, s20
	s_add_i32 s22, s21, 1
	s_cmp_ge_u32 s20, s11
	s_cselect_b32 s20, s22, s21
	s_xor_b32 s20, s20, s19
	s_waitcnt lgkmcnt(0)
	s_sub_i32 s20, s20, s19
	ds_read2_b32 v[96:97], v40 offset1:33
	s_mul_i32 s11, s20, s11
	s_waitcnt lgkmcnt(0)
	v_cvt_pk_bf16_f32 v96, v96, v97
	ds_read2_b32 v[98:99], v40 offset0:66 offset1:99
	s_sub_i32 s10, s10, s11
	s_waitcnt lgkmcnt(0)
	v_cvt_pk_bf16_f32 v97, v98, v99
	ds_read2_b32 v[98:99], v40 offset0:132 offset1:165
	s_lshl_b32 s19, s10, 5
	s_waitcnt lgkmcnt(0)
	v_cvt_pk_bf16_f32 v98, v98, v99
	ds_read2_b32 v[100:101], v40 offset0:198 offset1:231
	s_waitcnt lgkmcnt(0)
	v_cvt_pk_bf16_f32 v99, v100, v101
	v_or_b32_e32 v100, s19, v39
	s_lshl_b32 s10, s20, 6
	v_ashrrev_i32_e32 v101, 31, v100
	s_ashr_i32 s11, s10, 31
	v_lshlrev_b64 v[100:101], 11, v[100:101]
	v_lshl_add_u64 v[100:101], s[4:5], 0, v[100:101]
	s_lshl_b64 s[10:11], s[10:11], 1
	v_lshl_add_u64 v[100:101], v[100:101], 0, s[10:11]
	v_mov_b32_e32 v35, v1
	v_lshl_add_u64 v[100:101], v[100:101], 0, v[34:35]
	global_store_dwordx4 v[100:101], v[96:99], off nt
	ds_read2_b32 v[96:97], v40 offset0:8 offset1:41
	s_and_b64 vcc, exec, s[8:9]
	s_waitcnt lgkmcnt(0)
	v_cvt_pk_bf16_f32 v96, v96, v97
	ds_read2_b32 v[98:99], v40 offset0:74 offset1:107
	s_waitcnt lgkmcnt(0)
	v_cvt_pk_bf16_f32 v97, v98, v99
	ds_read2_b32 v[98:99], v40 offset0:140 offset1:173
	s_waitcnt lgkmcnt(0)
	v_cvt_pk_bf16_f32 v98, v98, v99
	ds_read2_b32 v[100:101], v40 offset0:206 offset1:239
	s_waitcnt lgkmcnt(0)
	v_cvt_pk_bf16_f32 v99, v100, v101
	v_or_b32_e32 v100, s19, v41
	v_ashrrev_i32_e32 v101, 31, v100
	v_lshlrev_b64 v[100:101], 11, v[100:101]
	v_lshl_add_u64 v[100:101], s[4:5], 0, v[100:101]
	v_lshl_add_u64 v[100:101], v[100:101], 0, s[10:11]
	v_lshl_add_u64 v[100:101], v[100:101], 0, v[34:35]
	global_store_dwordx4 v[100:101], v[96:99], off nt
	ds_read2_b32 v[96:97], v40 offset0:16 offset1:49
	s_waitcnt lgkmcnt(0)
	v_cvt_pk_bf16_f32 v96, v96, v97
	ds_read2_b32 v[98:99], v40 offset0:82 offset1:115
	s_waitcnt lgkmcnt(0)
	v_cvt_pk_bf16_f32 v97, v98, v99
	ds_read2_b32 v[98:99], v40 offset0:148 offset1:181
	s_waitcnt lgkmcnt(0)
	v_cvt_pk_bf16_f32 v98, v98, v99
	ds_read2_b32 v[100:101], v40 offset0:214 offset1:247
	s_waitcnt lgkmcnt(0)
	v_cvt_pk_bf16_f32 v99, v100, v101
	v_or_b32_e32 v100, s19, v42
	v_ashrrev_i32_e32 v101, 31, v100
	v_lshlrev_b64 v[100:101], 11, v[100:101]
	v_lshl_add_u64 v[100:101], s[4:5], 0, v[100:101]
	v_lshl_add_u64 v[100:101], v[100:101], 0, s[10:11]
	v_lshl_add_u64 v[100:101], v[100:101], 0, v[34:35]
	global_store_dwordx4 v[100:101], v[96:99], off nt
	ds_read2_b32 v[96:97], v40 offset0:24 offset1:57
	s_waitcnt lgkmcnt(0)
	v_cvt_pk_bf16_f32 v96, v96, v97
	ds_read2_b32 v[98:99], v40 offset0:90 offset1:123
	s_waitcnt lgkmcnt(0)
	v_cvt_pk_bf16_f32 v97, v98, v99
	ds_read2_b32 v[98:99], v40 offset0:156 offset1:189
	s_waitcnt lgkmcnt(0)
	v_cvt_pk_bf16_f32 v98, v98, v99
	ds_read2_b32 v[100:101], v40 offset0:222 offset1:255
	s_waitcnt lgkmcnt(0)
	v_cvt_pk_bf16_f32 v99, v100, v101
	v_or_b32_e32 v100, s19, v43
	v_ashrrev_i32_e32 v101, 31, v100
	v_lshlrev_b64 v[100:101], 11, v[100:101]
	v_lshl_add_u64 v[100:101], s[4:5], 0, v[100:101]
	v_lshl_add_u64 v[100:101], v[100:101], 0, s[10:11]
	v_lshl_add_u64 v[100:101], v[100:101], 0, v[34:35]
	global_store_dwordx4 v[100:101], v[96:99], off nt
	s_waitcnt lgkmcnt(0)
	s_waitcnt vmcnt(35)
	v_mul_f32_e32 v2, v3, v9
	s_waitcnt vmcnt(34)
	v_mul_f32_e32 v3, v8, v10
	s_waitcnt vmcnt(33)
	v_mul_f32_e32 v4, v12, v13
	s_waitcnt vmcnt(32)
	v_mul_f32_e32 v5, v11, v14
	s_waitcnt vmcnt(31)
	v_mul_f32_e32 v6, v16, v17
	s_waitcnt vmcnt(30)
	v_mul_f32_e32 v7, v15, v18
	s_waitcnt vmcnt(29)
	v_mul_f32_e32 v8, v20, v21
	s_waitcnt vmcnt(28)
	v_mul_f32_e32 v9, v19, v22
	s_waitcnt vmcnt(27)
	v_mul_f32_e32 v10, v24, v25
	s_waitcnt vmcnt(26)
	v_mul_f32_e32 v11, v23, v26
	s_waitcnt vmcnt(25)
	v_mul_f32_e32 v12, v28, v29
	s_waitcnt vmcnt(24)
	v_mul_f32_e32 v13, v27, v30
	s_waitcnt vmcnt(23)
	v_mul_f32_e32 v14, v32, v33
	s_waitcnt vmcnt(22)
	v_mul_f32_e32 v15, v31, v94
	s_waitcnt vmcnt(21)
	v_mul_f32_e32 v16, v46, v47
	s_waitcnt vmcnt(20)
	v_mul_f32_e32 v17, v45, v48
	s_waitcnt vmcnt(19)
	v_mul_f32_e32 v18, v50, v51
	s_waitcnt vmcnt(18)
	v_mul_f32_e32 v19, v49, v52
	s_waitcnt vmcnt(17)
	v_mul_f32_e32 v20, v54, v55
	s_waitcnt vmcnt(16)
	v_mul_f32_e32 v21, v53, v56
	s_waitcnt vmcnt(15)
	v_mul_f32_e32 v22, v58, v59
	s_waitcnt vmcnt(14)
	v_mul_f32_e32 v23, v57, v60
	s_waitcnt vmcnt(13)
	v_mul_f32_e32 v24, v62, v63
	s_waitcnt vmcnt(12)
	v_mul_f32_e32 v25, v61, v64
	s_waitcnt vmcnt(11)
	v_mul_f32_e32 v26, v66, v67
	s_waitcnt vmcnt(10)
	v_mul_f32_e32 v27, v65, v68
	s_waitcnt vmcnt(9)
	v_mul_f32_e32 v28, v70, v71
	s_waitcnt vmcnt(8)
	v_mul_f32_e32 v29, v69, v72
	s_waitcnt vmcnt(7)
	v_mul_f32_e32 v30, v74, v75
	s_waitcnt vmcnt(6)
	v_mul_f32_e32 v31, v73, v77
	s_waitcnt vmcnt(5)
	v_mul_f32_e32 v32, v78, v79
	s_waitcnt vmcnt(4)
	v_mul_f32_e32 v33, v76, v80
	s_mov_b32 s19, s18
	s_cbranch_vccnz .LBB0_300

.LBB0_371:
	s_cmpk_lt_i32 s18, 0xc00
	s_cselect_b32 s11, 0xc0, 32
	v_cvt_f32_ubyte0_e32 v35, s11
	v_rcp_iflag_f32_e32 v35, v35
	s_cselect_b32 s19, 0x400, s95
	s_cselect_b32 s5, s97, s77
	s_cselect_b32 s4, s89, s76
	v_mul_f32_e32 v35, 0x4f7ffffe, v35
	v_cvt_u32_f32_e32 v35, v35
	s_cselect_b32 s10, 0, 0xfffff400
	s_sub_i32 s21, 0, s11
	s_add_i32 s10, s10, s18
	v_readfirstlane_b32 s22, v35
	s_mul_i32 s21, s21, s22
	s_mul_hi_u32 s21, s22, s21
	s_abs_i32 s20, s10
	s_add_i32 s22, s22, s21
	s_mul_hi_u32 s21, s20, s22
	s_mul_i32 s22, s21, s11
	s_sub_i32 s20, s20, s22
	s_ashr_i32 s18, s10, 31
	s_add_i32 s22, s21, 1
	s_sub_i32 s23, s20, s11
	s_cmp_ge_u32 s20, s11
	s_cselect_b32 s21, s22, s21
	s_cselect_b32 s20, s23, s20
	s_add_i32 s22, s21, 1
	s_cmp_ge_u32 s20, s11
	s_cselect_b32 s20, s22, s21
	s_xor_b32 s20, s20, s18
	s_sub_i32 s20, s20, s18
	s_waitcnt lgkmcnt(0)
	s_mul_i32 s11, s20, s11
	ds_read2_b32 v[96:97], v39 offset1:33
	s_sub_i32 s10, s10, s11
	s_waitcnt lgkmcnt(0)
	v_cvt_pk_bf16_f32 v96, v96, v97
	ds_read2_b32 v[98:99], v39 offset0:66 offset1:99
	s_lshl_b32 s18, s10, 5
	s_waitcnt lgkmcnt(0)
	v_cvt_pk_bf16_f32 v97, v98, v99
	ds_read2_b32 v[98:99], v39 offset0:132 offset1:165
	s_lshl_b32 s10, s20, 6
	s_waitcnt lgkmcnt(0)
	v_cvt_pk_bf16_f32 v98, v98, v99
	ds_read2_b32 v[100:101], v39 offset0:198 offset1:231
	v_or_b32_e32 v35, s18, v37
	s_ashr_i32 s11, s10, 31
	s_waitcnt lgkmcnt(0)
	v_cvt_pk_bf16_f32 v99, v100, v101
	v_mad_i64_i32 v[100:101], s[20:21], s19, v35, 0
	v_lshl_add_u64 v[100:101], v[100:101], 1, s[4:5]
	s_lshl_b64 s[10:11], s[10:11], 1
	v_lshl_add_u64 v[100:101], v[100:101], 0, s[10:11]
	v_mov_b32_e32 v35, v1
	v_lshl_add_u64 v[100:101], v[100:101], 0, v[34:35]
	global_store_dwordx4 v[100:101], v[96:99], off nt
	ds_read2_b32 v[96:97], v39 offset0:8 offset1:41
	s_andn2_b64 vcc, exec, s[8:9]
	s_waitcnt lgkmcnt(0)
	v_cvt_pk_bf16_f32 v96, v96, v97
	ds_read2_b32 v[98:99], v39 offset0:74 offset1:107
	s_waitcnt lgkmcnt(0)
	v_cvt_pk_bf16_f32 v97, v98, v99
	ds_read2_b32 v[98:99], v39 offset0:140 offset1:173
	s_waitcnt lgkmcnt(0)
	v_cvt_pk_bf16_f32 v98, v98, v99
	ds_read2_b32 v[100:101], v39 offset0:206 offset1:239
	s_waitcnt lgkmcnt(0)
	v_cvt_pk_bf16_f32 v99, v100, v101
	v_or_b32_e32 v100, s18, v40
	v_mad_i64_i32 v[100:101], s[20:21], s19, v100, 0
	v_lshl_add_u64 v[100:101], v[100:101], 1, s[4:5]
	v_lshl_add_u64 v[100:101], v[100:101], 0, s[10:11]
	v_lshl_add_u64 v[100:101], v[100:101], 0, v[34:35]
	global_store_dwordx4 v[100:101], v[96:99], off nt
	ds_read2_b32 v[96:97], v39 offset0:16 offset1:49
	s_waitcnt lgkmcnt(0)
	v_cvt_pk_bf16_f32 v96, v96, v97
	ds_read2_b32 v[98:99], v39 offset0:82 offset1:115
	s_waitcnt lgkmcnt(0)
	v_cvt_pk_bf16_f32 v97, v98, v99
	ds_read2_b32 v[98:99], v39 offset0:148 offset1:181
	s_waitcnt lgkmcnt(0)
	v_cvt_pk_bf16_f32 v98, v98, v99
	ds_read2_b32 v[100:101], v39 offset0:214 offset1:247
	s_waitcnt lgkmcnt(0)
	v_cvt_pk_bf16_f32 v99, v100, v101
	v_or_b32_e32 v100, s18, v41
	v_mad_i64_i32 v[100:101], s[20:21], s19, v100, 0
	v_lshl_add_u64 v[100:101], v[100:101], 1, s[4:5]
	v_lshl_add_u64 v[100:101], v[100:101], 0, s[10:11]
	v_lshl_add_u64 v[100:101], v[100:101], 0, v[34:35]
	global_store_dwordx4 v[100:101], v[96:99], off nt
	ds_read2_b32 v[96:97], v39 offset0:24 offset1:57
	s_waitcnt lgkmcnt(0)
	v_cvt_pk_bf16_f32 v96, v96, v97
	ds_read2_b32 v[98:99], v39 offset0:90 offset1:123
	s_waitcnt lgkmcnt(0)
	v_cvt_pk_bf16_f32 v97, v98, v99
	ds_read2_b32 v[98:99], v39 offset0:156 offset1:189
	s_waitcnt lgkmcnt(0)
	v_cvt_pk_bf16_f32 v98, v98, v99
	ds_read2_b32 v[100:101], v39 offset0:222 offset1:255
	s_waitcnt lgkmcnt(0)
	v_cvt_pk_bf16_f32 v99, v100, v101
	v_or_b32_e32 v100, s18, v42
	v_mad_i64_i32 v[100:101], s[18:19], s19, v100, 0
	v_lshl_add_u64 v[100:101], v[100:101], 1, s[4:5]
	v_lshl_add_u64 v[100:101], v[100:101], 0, s[10:11]
	v_lshl_add_u64 v[100:101], v[100:101], 0, v[34:35]
	global_store_dwordx4 v[100:101], v[96:99], off nt
	s_waitcnt lgkmcnt(0)
	s_waitcnt vmcnt(35)
	v_mul_f32_e32 v2, v3, v9
	s_waitcnt vmcnt(34)
	v_mul_f32_e32 v3, v8, v10
	s_waitcnt vmcnt(33)
	v_mul_f32_e32 v4, v12, v13
	s_waitcnt vmcnt(32)
	v_mul_f32_e32 v5, v11, v14
	s_waitcnt vmcnt(31)
	v_mul_f32_e32 v6, v16, v17
	s_waitcnt vmcnt(30)
	v_mul_f32_e32 v7, v15, v18
	s_waitcnt vmcnt(29)
	v_mul_f32_e32 v8, v20, v21
	s_waitcnt vmcnt(28)
	v_mul_f32_e32 v9, v19, v22
	s_waitcnt vmcnt(27)
	v_mul_f32_e32 v10, v24, v25
	s_waitcnt vmcnt(26)
	v_mul_f32_e32 v11, v23, v26
	s_waitcnt vmcnt(25)
	v_mul_f32_e32 v12, v28, v29
	s_waitcnt vmcnt(24)
	v_mul_f32_e32 v13, v27, v30
	s_waitcnt vmcnt(23)
	v_mul_f32_e32 v14, v32, v33
	s_waitcnt vmcnt(22)
	v_mul_f32_e32 v15, v31, v94
	s_waitcnt vmcnt(21)
	v_mul_f32_e32 v16, v45, v46
	s_waitcnt vmcnt(20)
	v_mul_f32_e32 v17, v44, v47
	s_waitcnt vmcnt(19)
	v_mul_f32_e32 v18, v49, v50
	s_waitcnt vmcnt(18)
	v_mul_f32_e32 v19, v48, v51
	s_waitcnt vmcnt(17)
	v_mul_f32_e32 v20, v53, v54
	s_waitcnt vmcnt(16)
	v_mul_f32_e32 v21, v52, v55
	s_waitcnt vmcnt(15)
	v_mul_f32_e32 v22, v57, v58
	s_waitcnt vmcnt(14)
	v_mul_f32_e32 v23, v56, v59
	s_waitcnt vmcnt(13)
	v_mul_f32_e32 v24, v61, v62
	s_waitcnt vmcnt(12)
	v_mul_f32_e32 v25, v60, v63
	s_waitcnt vmcnt(11)
	v_mul_f32_e32 v26, v65, v66
	s_waitcnt vmcnt(10)
	v_mul_f32_e32 v27, v64, v67
	s_waitcnt vmcnt(9)
	v_mul_f32_e32 v28, v69, v70
	s_waitcnt vmcnt(8)
	v_mul_f32_e32 v29, v68, v71
	s_waitcnt vmcnt(7)
	v_mul_f32_e32 v30, v73, v74
	s_waitcnt vmcnt(6)
	v_mul_f32_e32 v31, v72, v76
	s_waitcnt vmcnt(5)
	v_mul_f32_e32 v32, v77, v78
	s_waitcnt vmcnt(4)
	v_mul_f32_e32 v33, v75, v79
	s_mov_b32 s18, s13
	s_cbranch_vccz .LBB0_437

.LBB0_611:
	s_and_b64 s[4:5], s[4:5], exec
	s_movk_i32 s4, 0x400
	s_cselect_b32 s18, s4, 0xb00
	s_mov_b32 s4, 0x1c00000
	v_add_u32_e32 v95, s12, v37
	s_cselect_b32 s4, s4, 0x2700000
	s_add_u32 s4, s36, s4
	v_mad_i64_i32 v[100:101], s[20:21], s18, v95, 0
	ds_read2_b32 v[96:97], v38 offset1:33
	s_addc_u32 s5, s37, 0
	s_lshl_b32 s20, s13, 6
	s_waitcnt lgkmcnt(0)
	v_cvt_pk_bf16_f32 v96, v96, v97
	ds_read2_b32 v[98:99], v38 offset0:66 offset1:99
	s_ashr_i32 s21, s20, 31
	s_waitcnt lgkmcnt(0)
	v_cvt_pk_bf16_f32 v97, v98, v99
	ds_read2_b32 v[98:99], v38 offset0:132 offset1:165
	v_lshl_add_u64 v[100:101], v[100:101], 1, s[4:5]
	s_lshl_b64 s[20:21], s[20:21], 1
	v_mov_b32_e32 v35, v1
	s_waitcnt lgkmcnt(0)
	v_cvt_pk_bf16_f32 v98, v98, v99
	ds_read2_b32 v[102:103], v38 offset0:198 offset1:231
	v_lshl_add_u64 v[100:101], v[100:101], 0, s[20:21]
	s_waitcnt lgkmcnt(0)
	v_cvt_pk_bf16_f32 v99, v102, v103
	ds_read2_b32 v[102:103], v38 offset0:8 offset1:41
	v_lshl_add_u64 v[100:101], v[100:101], 0, v[34:35]
	v_add_u32_e32 v95, s12, v39
	global_store_dwordx4 v[100:101], v[96:99], off nt
	s_andn2_b64 vcc, exec, s[10:11]
	s_waitcnt lgkmcnt(0)
	v_cvt_pk_bf16_f32 v96, v102, v103
	v_mad_i64_i32 v[102:103], s[22:23], s18, v95, 0
	v_lshl_add_u64 v[102:103], v[102:103], 1, s[4:5]
	ds_read2_b32 v[98:99], v38 offset0:74 offset1:107
	v_lshl_add_u64 v[102:103], v[102:103], 0, s[20:21]
	s_waitcnt lgkmcnt(0)
	v_cvt_pk_bf16_f32 v97, v98, v99
	ds_read2_b32 v[98:99], v38 offset0:140 offset1:173
	v_lshl_add_u64 v[102:103], v[102:103], 0, v[34:35]
	v_add_u32_e32 v95, s12, v40
	s_waitcnt lgkmcnt(0)
	v_cvt_pk_bf16_f32 v98, v98, v99
	ds_read2_b32 v[100:101], v38 offset0:206 offset1:239
	s_waitcnt lgkmcnt(0)
	v_cvt_pk_bf16_f32 v99, v100, v101
	global_store_dwordx4 v[102:103], v[96:99], off nt
	v_mad_i64_i32 v[102:103], s[22:23], s18, v95, 0
	v_lshl_add_u64 v[102:103], v[102:103], 1, s[4:5]
	ds_read2_b32 v[100:101], v38 offset0:16 offset1:49
	s_waitcnt lgkmcnt(0)
	v_cvt_pk_bf16_f32 v96, v100, v101
	ds_read2_b32 v[98:99], v38 offset0:82 offset1:115
	v_lshl_add_u64 v[102:103], v[102:103], 0, s[20:21]
	s_waitcnt lgkmcnt(0)
	v_cvt_pk_bf16_f32 v97, v98, v99
	ds_read2_b32 v[98:99], v38 offset0:148 offset1:181
	v_lshl_add_u64 v[102:103], v[102:103], 0, v[34:35]
	v_add_u32_e32 v95, s12, v41
	s_waitcnt lgkmcnt(0)
	v_cvt_pk_bf16_f32 v98, v98, v99
	ds_read2_b32 v[100:101], v38 offset0:214 offset1:247
	s_waitcnt lgkmcnt(0)
	v_cvt_pk_bf16_f32 v99, v100, v101
	global_store_dwordx4 v[102:103], v[96:99], off nt
	v_mad_i64_i32 v[102:103], s[12:13], s18, v95, 0
	v_lshl_add_u64 v[102:103], v[102:103], 1, s[4:5]
	ds_read2_b32 v[100:101], v38 offset0:24 offset1:57
	s_waitcnt lgkmcnt(0)
	v_cvt_pk_bf16_f32 v96, v100, v101
	ds_read2_b32 v[98:99], v38 offset0:90 offset1:123
	v_lshl_add_u64 v[102:103], v[102:103], 0, s[20:21]
	s_waitcnt lgkmcnt(0)
	v_cvt_pk_bf16_f32 v97, v98, v99
	ds_read2_b32 v[98:99], v38 offset0:156 offset1:189
	v_lshl_add_u64 v[102:103], v[102:103], 0, v[34:35]
	s_waitcnt lgkmcnt(0)
	v_cvt_pk_bf16_f32 v98, v98, v99
	ds_read2_b32 v[100:101], v38 offset0:222 offset1:255
	s_waitcnt lgkmcnt(0)
	v_cvt_pk_bf16_f32 v99, v100, v101
	global_store_dwordx4 v[102:103], v[96:99], off nt
	s_waitcnt lgkmcnt(0)
	s_waitcnt vmcnt(35)
	v_mul_f32_e32 v2, v3, v9
	s_waitcnt vmcnt(34)
	v_mul_f32_e32 v3, v8, v10
	s_waitcnt vmcnt(33)
	v_mul_f32_e32 v4, v12, v13
	s_waitcnt vmcnt(32)
	v_mul_f32_e32 v5, v11, v14
	s_waitcnt vmcnt(31)
	v_mul_f32_e32 v6, v16, v17
	s_waitcnt vmcnt(30)
	v_mul_f32_e32 v7, v15, v18
	s_waitcnt vmcnt(29)
	v_mul_f32_e32 v8, v20, v21
	s_waitcnt vmcnt(28)
	v_mul_f32_e32 v9, v19, v22
	s_waitcnt vmcnt(27)
	v_mul_f32_e32 v10, v24, v25
	s_waitcnt vmcnt(26)
	v_mul_f32_e32 v11, v23, v26
	s_waitcnt vmcnt(25)
	v_mul_f32_e32 v12, v28, v29
	s_waitcnt vmcnt(24)
	v_mul_f32_e32 v13, v27, v30
	s_waitcnt vmcnt(23)
	v_mul_f32_e32 v14, v32, v33
	s_waitcnt vmcnt(22)
	v_mul_f32_e32 v15, v31, v94
	s_waitcnt vmcnt(21)
	v_mul_f32_e32 v16, v44, v45
	s_waitcnt vmcnt(20)
	v_mul_f32_e32 v17, v43, v46
	s_waitcnt vmcnt(19)
	v_mul_f32_e32 v18, v48, v49
	s_waitcnt vmcnt(18)
	v_mul_f32_e32 v19, v47, v50
	s_waitcnt vmcnt(17)
	v_mul_f32_e32 v20, v52, v53
	s_waitcnt vmcnt(16)
	v_mul_f32_e32 v21, v51, v54
	s_waitcnt vmcnt(15)
	v_mul_f32_e32 v22, v56, v57
	s_waitcnt vmcnt(14)
	v_mul_f32_e32 v23, v55, v58
	s_waitcnt vmcnt(13)
	v_mul_f32_e32 v24, v60, v61
	s_waitcnt vmcnt(12)
	v_mul_f32_e32 v25, v59, v62
	s_waitcnt vmcnt(11)
	v_mul_f32_e32 v26, v64, v65
	s_waitcnt vmcnt(10)
	v_mul_f32_e32 v27, v63, v66
	s_waitcnt vmcnt(9)
	v_mul_f32_e32 v28, v68, v69
	s_waitcnt vmcnt(8)
	v_mul_f32_e32 v29, v67, v70
	s_waitcnt vmcnt(7)
	v_mul_f32_e32 v30, v72, v73
	s_waitcnt vmcnt(6)
	v_mul_f32_e32 v31, v71, v75
	s_waitcnt vmcnt(5)
	v_mul_f32_e32 v32, v76, v77
	s_waitcnt vmcnt(4)
	v_mul_f32_e32 v33, v74, v78
	s_mov_b32 s18, s19
	s_cbranch_vccz .Lmy_cvf_end
